# v18 + per-group start skew (0..5us by grp&3) in the layer-1 tail to de-phase store bursts
# speedup vs baseline: 1.0019x; 1.0019x over previous
.LBB0_907:
	s_cmp_lt_i32 s76, 6
	s_cselect_b64 s[2:3], -1, 0
	s_and_b64 s[0:1], s[2:3], s[0:1]
	s_andn2_b64 vcc, exec, s[0:1]
	s_cbranch_vccnz .LBB0_1023
	s_and_b32 s100, s40, 3
.Lskew_p5:
	s_cmp_eq_u32 s100, 0
	s_cbranch_scc1 .Lskew_done_p5
	s_sleep 56
	s_sub_u32 s100, s100, 1
	s_branch .Lskew_p5
.Lskew_done_p5:
	s_cmpk_gt_u32 s88, 0xdf
	s_cbranch_scc0 .LBB0_910
	s_lshl_b32 s0, s40, 1
	s_addk_i32 s0, 0xff91
	s_mov_b32 s1, 0
	s_lshl_b64 s[0:1], s[0:1], 20
	s_add_u32 s44, s96, s0
	s_addc_u32 s45, s97, s1
	s_cbranch_execz .LBB0_911
	s_branch .LBB0_912

	.amdhsa_kernel _Z8mega_fwd4Args
		.amdhsa_group_segment_fixed_size 0
		.amdhsa_private_segment_fixed_size 0
		.amdhsa_kernarg_size 424
		.amdhsa_user_sgpr_count 2
		.amdhsa_user_sgpr_dispatch_ptr 0
		.amdhsa_user_sgpr_queue_ptr 0
		.amdhsa_user_sgpr_kernarg_segment_ptr 1
		.amdhsa_user_sgpr_dispatch_id 0
		.amdhsa_user_sgpr_kernarg_preload_length 0
		.amdhsa_user_sgpr_kernarg_preload_offset 0
		.amdhsa_user_sgpr_private_segment_size 0
		.amdhsa_uses_dynamic_stack 0
		.amdhsa_enable_private_segment 0
		.amdhsa_system_sgpr_workgroup_id_x 1
		.amdhsa_system_sgpr_workgroup_id_y 0
		.amdhsa_system_sgpr_workgroup_id_z 0
		.amdhsa_system_sgpr_workgroup_info 0
		.amdhsa_system_vgpr_workitem_id 2
		.amdhsa_next_free_vgpr 255
		.amdhsa_next_free_sgpr 102
		.amdhsa_accum_offset 256
		.amdhsa_reserve_vcc 1
		.amdhsa_float_round_mode_32 0
		.amdhsa_float_round_mode_16_64 0
		.amdhsa_float_denorm_mode_32 3
		.amdhsa_float_denorm_mode_16_64 3
		.amdhsa_dx10_clamp 1
		.amdhsa_ieee_mode 1
		.amdhsa_fp16_overflow 0
		.amdhsa_tg_split 0
		.amdhsa_exception_fp_ieee_invalid_op 0
		.amdhsa_exception_fp_denorm_src 0
		.amdhsa_exception_fp_ieee_div_zero 0
		.amdhsa_exception_fp_ieee_overflow 0
		.amdhsa_exception_fp_ieee_underflow 0
		.amdhsa_exception_fp_ieee_inexact 0
		.amdhsa_exception_int_div_zero 0
	.end_amdhsa_kernel

amdhsa.kernels:
  - .agpr_count:     0
    .args:
      - .offset:         0
        .size:           168
        .value_kind:     by_value
      - .offset:         168
        .size:           4
        .value_kind:     hidden_block_count_x
      - .offset:         172
        .size:           4
        .value_kind:     hidden_block_count_y
      - .offset:         176
        .size:           4
        .value_kind:     hidden_block_count_z
      - .offset:         180
        .size:           2
        .value_kind:     hidden_group_size_x
      - .offset:         182
        .size:           2
        .value_kind:     hidden_group_size_y
      - .offset:         184
        .size:           2
        .value_kind:     hidden_group_size_z
      - .offset:         186
        .size:           2
        .value_kind:     hidden_remainder_x
      - .offset:         188
        .size:           2
        .value_kind:     hidden_remainder_y
      - .offset:         190
        .size:           2
        .value_kind:     hidden_remainder_z
      - .offset:         208
        .size:           8
        .value_kind:     hidden_global_offset_x
      - .offset:         216
        .size:           8
        .value_kind:     hidden_global_offset_y
      - .offset:         224
        .size:           8
        .value_kind:     hidden_global_offset_z
      - .offset:         232
        .size:           2
        .value_kind:     hidden_grid_dims
      - .offset:         256
        .size:           8
        .value_kind:     hidden_multigrid_sync_arg
      - .offset:         288
        .size:           4
        .value_kind:     hidden_dynamic_lds_size
    .group_segment_fixed_size: 0
    .kernarg_segment_align: 8
    .kernarg_segment_size: 424
    .language:       OpenCL C
    .language_version:
      - 2
      - 0
    .max_flat_workgroup_size: 512
    .name:           _Z8mega_fwd4Args
    .private_segment_fixed_size: 0
    .sgpr_count:     108
    .sgpr_spill_count: 55
    .symbol:         _Z8mega_fwd4Args.kd
    .uniform_work_group_size: 1
    .uses_dynamic_stack: false
    .vgpr_count:     255
    .vgpr_spill_count: 0
    .wavefront_size: 64
